# grid-barrier polling loops: back-off s_sleep 1 -> s_sleep 4 (121 sites) to reduce polling contention on the barrier counters
# speedup vs baseline: 1.0057x; 1.0057x over previous
.LBB0_102:
	s_sleep 4
	global_load_dword v2, v0, s[2:3] offset:32 sc1
	s_waitcnt vmcnt(0)
	v_and_b32_e32 v2, 0xffff0000, v2
	v_cmp_ne_u32_e32 vcc, v2, v1
	s_or_b64 s[6:7], vcc, s[6:7]
	s_andn2_b64 exec, exec, s[6:7]
	s_cbranch_execnz .LBB0_102

.LBB0_110:
	global_load_dword v16, v15, s[50:51] offset:256 sc1
	global_load_dword v14, v15, s[50:51] offset:512 sc1
	global_load_dword v13, v15, s[50:51] offset:768 sc1
	global_load_dword v12, v15, s[50:51] offset:1024 sc1
	global_load_dword v11, v15, s[50:51] offset:1280 sc1
	global_load_dword v10, v15, s[50:51] offset:1536 sc1
	global_load_dword v9, v15, s[50:51] offset:1792 sc1
	global_load_dword v8, v15, s[50:51] offset:2048 sc1
	global_load_dword v7, v15, s[50:51] offset:2304 sc1
	global_load_dword v6, v15, s[50:51] offset:2560 sc1
	global_load_dword v5, v15, s[50:51] offset:2816 sc1
	global_load_dword v4, v15, s[50:51] offset:3072 sc1
	global_load_dword v3, v15, s[50:51] offset:3328 sc1
	global_load_dword v2, v15, s[50:51] offset:3584 sc1
	global_load_dword v1, v15, s[50:51] offset:3840 sc1
	global_load_dword v0, v15, s[6:7] sc1
	s_load_dword s8, s[0:1], 0x170
	s_waitcnt vmcnt(14)
	v_add_u32_e32 v17, v14, v16
	s_waitcnt vmcnt(13)
	v_add_u32_e32 v17, v17, v13
	s_waitcnt vmcnt(12)
	v_add_u32_e32 v17, v17, v12
	s_waitcnt vmcnt(11)
	v_add_u32_e32 v17, v17, v11
	s_waitcnt vmcnt(10)
	v_add_u32_e32 v17, v17, v10
	s_waitcnt vmcnt(9)
	v_add_u32_e32 v17, v17, v9
	s_waitcnt vmcnt(8)
	v_add_u32_e32 v17, v17, v8
	s_waitcnt vmcnt(7)
	v_add_u32_e32 v17, v17, v7
	s_waitcnt vmcnt(6)
	v_add_u32_e32 v17, v17, v6
	s_waitcnt vmcnt(5)
	v_add_u32_e32 v17, v17, v5
	s_waitcnt vmcnt(4)
	v_add_u32_e32 v17, v17, v4
	s_waitcnt vmcnt(3)
	v_add_u32_e32 v17, v17, v3
	s_waitcnt vmcnt(2)
	v_add_u32_e32 v17, v17, v2
	s_waitcnt vmcnt(1)
	v_add_u32_e32 v17, v17, v1
	s_waitcnt vmcnt(0)
	v_add_u32_e32 v17, v17, v0
	s_waitcnt lgkmcnt(0)
	v_cmp_eq_u32_e32 vcc, s8, v17
	s_mov_b64 s[8:9], -1
	s_cbranch_vccnz .LBB0_108
	s_cmp_lg_u32 s11, 0
	s_sleep 4
	s_cbranch_scc0 .LBB0_108
	global_load_dword v16, v15, s[50:51] offset:256 sc1
	global_load_dword v14, v15, s[50:51] offset:512 sc1
	global_load_dword v13, v15, s[50:51] offset:768 sc1
	global_load_dword v12, v15, s[50:51] offset:1024 sc1
	global_load_dword v11, v15, s[50:51] offset:1280 sc1
	global_load_dword v10, v15, s[50:51] offset:1536 sc1
	global_load_dword v9, v15, s[50:51] offset:1792 sc1
	global_load_dword v8, v15, s[50:51] offset:2048 sc1
	global_load_dword v7, v15, s[50:51] offset:2304 sc1
	global_load_dword v6, v15, s[50:51] offset:2560 sc1
	global_load_dword v5, v15, s[50:51] offset:2816 sc1
	global_load_dword v4, v15, s[50:51] offset:3072 sc1
	global_load_dword v3, v15, s[50:51] offset:3328 sc1
	global_load_dword v2, v15, s[50:51] offset:3584 sc1
	global_load_dword v1, v15, s[50:51] offset:3840 sc1
	global_load_dword v0, v15, s[6:7] sc1
	s_load_dword s8, s[0:1], 0x170
	s_waitcnt vmcnt(14)
	v_add_u32_e32 v17, v14, v16
	s_waitcnt vmcnt(13)
	v_add_u32_e32 v17, v17, v13
	s_waitcnt vmcnt(12)
	v_add_u32_e32 v17, v17, v12
	s_waitcnt vmcnt(11)
	v_add_u32_e32 v17, v17, v11
	s_waitcnt vmcnt(10)
	v_add_u32_e32 v17, v17, v10
	s_waitcnt vmcnt(9)
	v_add_u32_e32 v17, v17, v9
	s_waitcnt vmcnt(8)
	v_add_u32_e32 v17, v17, v8
	s_waitcnt vmcnt(7)
	v_add_u32_e32 v17, v17, v7
	s_waitcnt vmcnt(6)
	v_add_u32_e32 v17, v17, v6
	s_waitcnt vmcnt(5)
	v_add_u32_e32 v17, v17, v5
	s_waitcnt vmcnt(4)
	v_add_u32_e32 v17, v17, v4
	s_waitcnt vmcnt(3)
	v_add_u32_e32 v17, v17, v3
	s_waitcnt vmcnt(2)
	v_add_u32_e32 v17, v17, v2
	s_waitcnt vmcnt(1)
	v_add_u32_e32 v17, v17, v1
	s_waitcnt vmcnt(0)
	v_add_u32_e32 v17, v17, v0
	s_waitcnt lgkmcnt(0)
	v_cmp_ne_u32_e32 vcc, s8, v17
	s_mov_b64 s[8:9], -1
	s_cbranch_vccz .LBB0_109
	s_sleep 4
	s_add_i32 s11, s11, -2
	s_mov_b64 s[8:9], 0
	s_branch .LBB0_109

.LBB0_124:
	global_load_dword v2, v0, s[8:9] sc1
	s_or_b64 s[12:13], s[12:13], exec
	s_waitcnt vmcnt(0)
	v_cmp_eq_u32_e32 vcc, v2, v1
	s_and_saveexec_b64 s[14:15], vcc
	s_cbranch_execz .LBB0_123
	s_sleep 4
	global_load_dword v2, v0, s[8:9] sc1
	s_mov_b64 s[18:19], -1
	s_waitcnt vmcnt(0)
	v_cmp_eq_u32_e32 vcc, v2, v1
	s_and_saveexec_b64 s[16:17], vcc
	s_cbranch_execz .LBB0_122
	s_sleep 4
	global_load_dword v2, v0, s[8:9] sc1
	s_mov_b64 s[20:21], -1
	s_waitcnt vmcnt(0)
	v_cmp_eq_u32_e32 vcc, v2, v1
	s_and_saveexec_b64 s[18:19], vcc
	s_cbranch_execz .LBB0_121
	s_sleep 4
	global_load_dword v2, v0, s[8:9] sc1
	s_mov_b64 s[22:23], -1
	s_waitcnt vmcnt(0)
	v_cmp_eq_u32_e32 vcc, v2, v1
	s_and_saveexec_b64 s[20:21], vcc
	s_cbranch_execz .LBB0_120
	s_sleep 4
	global_load_dword v2, v0, s[8:9] sc1
	s_waitcnt vmcnt(0)
	v_cmp_eq_u32_e32 vcc, v2, v1
	s_and_saveexec_b64 s[24:25], vcc
	s_cbranch_execz .LBB0_119
	s_add_i32 s26, s26, -5
	s_cmp_eq_u32 s26, 0
	s_cselect_b64 s[22:23], -1, 0
	s_orn2_b64 s[22:23], s[22:23], exec
	s_sleep 4
	s_branch .LBB0_119

.LBB0_141:
	global_load_dword v2, v0, s[6:7] sc1
	s_or_b64 s[12:13], s[12:13], exec
	s_waitcnt vmcnt(0)
	v_cmp_eq_u32_e32 vcc, v2, v1
	s_and_saveexec_b64 s[14:15], vcc
	s_cbranch_execz .LBB0_140
	s_sleep 4
	global_load_dword v2, v0, s[6:7] sc1
	s_mov_b64 s[18:19], -1
	s_waitcnt vmcnt(0)
	v_cmp_eq_u32_e32 vcc, v2, v1
	s_and_saveexec_b64 s[16:17], vcc
	s_cbranch_execz .LBB0_139
	s_sleep 4
	global_load_dword v2, v0, s[6:7] sc1
	s_mov_b64 s[20:21], -1
	s_waitcnt vmcnt(0)
	v_cmp_eq_u32_e32 vcc, v2, v1
	s_and_saveexec_b64 s[18:19], vcc
	s_cbranch_execz .LBB0_138
	s_sleep 4
	global_load_dword v2, v0, s[6:7] sc1
	s_mov_b64 s[22:23], -1
	s_waitcnt vmcnt(0)
	v_cmp_eq_u32_e32 vcc, v2, v1
	s_and_saveexec_b64 s[20:21], vcc
	s_cbranch_execz .LBB0_137
	s_sleep 4
	global_load_dword v2, v0, s[6:7] sc1
	s_waitcnt vmcnt(0)
	v_cmp_eq_u32_e32 vcc, v2, v1
	s_and_saveexec_b64 s[24:25], vcc
	s_cbranch_execz .LBB0_136
	s_add_i32 s26, s26, -5
	s_cmp_eq_u32 s26, 0
	s_cselect_b64 s[22:23], -1, 0
	s_orn2_b64 s[22:23], s[22:23], exec
	s_sleep 4
	s_branch .LBB0_136

.LBB0_166:
	v_readlane_b32 s4, v254, 5
	global_load_dword v15, v177, s[50:51] offset:256 sc1
	global_load_dword v14, v177, s[50:51] offset:512 sc1
	global_load_dword v13, v177, s[50:51] offset:768 sc1
	global_load_dword v12, v177, s[50:51] offset:1024 sc1
	global_load_dword v11, v177, s[50:51] offset:1280 sc1
	global_load_dword v10, v177, s[50:51] offset:1536 sc1
	global_load_dword v9, v177, s[50:51] offset:1792 sc1
	global_load_dword v8, v177, s[50:51] offset:2048 sc1
	global_load_dword v7, v177, s[50:51] offset:2304 sc1
	global_load_dword v6, v177, s[50:51] offset:2560 sc1
	global_load_dword v5, v177, s[50:51] offset:2816 sc1
	global_load_dword v4, v177, s[50:51] offset:3072 sc1
	global_load_dword v2, v177, s[50:51] offset:3328 sc1
	global_load_dword v1, v177, s[50:51] offset:3584 sc1
	global_load_dword v0, v177, s[50:51] offset:3840 sc1
	v_readlane_b32 s5, v254, 6
	s_waitcnt vmcnt(13)
	v_add_u32_e32 v16, v14, v15
	s_nop 2
	global_load_dword v3, v177, s[4:5] sc1
	s_waitcnt vmcnt(13)
	v_add_u32_e32 v16, v16, v13
	s_waitcnt vmcnt(12)
	v_add_u32_e32 v16, v16, v12
	s_waitcnt vmcnt(11)
	v_add_u32_e32 v16, v16, v11
	s_waitcnt vmcnt(10)
	v_add_u32_e32 v16, v16, v10
	s_waitcnt vmcnt(9)
	v_add_u32_e32 v16, v16, v9
	s_waitcnt vmcnt(8)
	v_add_u32_e32 v16, v16, v8
	s_waitcnt vmcnt(7)
	v_add_u32_e32 v16, v16, v7
	s_waitcnt vmcnt(6)
	v_add_u32_e32 v16, v16, v6
	s_waitcnt vmcnt(5)
	v_add_u32_e32 v16, v16, v5
	s_waitcnt vmcnt(4)
	v_add_u32_e32 v16, v16, v4
	s_waitcnt vmcnt(3)
	v_add_u32_e32 v16, v16, v2
	s_waitcnt vmcnt(2)
	v_add_u32_e32 v16, v16, v1
	s_waitcnt vmcnt(1)
	v_add_u32_e32 v16, v16, v0
	v_readlane_b32 s4, v253, 1
	s_waitcnt vmcnt(0)
	v_add_u32_e32 v16, v16, v3
	v_cmp_eq_u32_e32 vcc, s4, v16
	s_mov_b64 s[4:5], -1
	s_cbranch_vccnz .LBB0_164
	s_cmp_lg_u32 s7, 0
	s_sleep 4
	s_cbranch_scc0 .LBB0_164
	v_readlane_b32 s4, v254, 5
	global_load_dword v15, v177, s[50:51] offset:256 sc1
	global_load_dword v14, v177, s[50:51] offset:512 sc1
	global_load_dword v13, v177, s[50:51] offset:768 sc1
	global_load_dword v12, v177, s[50:51] offset:1024 sc1
	global_load_dword v11, v177, s[50:51] offset:1280 sc1
	global_load_dword v10, v177, s[50:51] offset:1536 sc1
	global_load_dword v9, v177, s[50:51] offset:1792 sc1
	global_load_dword v8, v177, s[50:51] offset:2048 sc1
	global_load_dword v7, v177, s[50:51] offset:2304 sc1
	global_load_dword v6, v177, s[50:51] offset:2560 sc1
	global_load_dword v5, v177, s[50:51] offset:2816 sc1
	global_load_dword v4, v177, s[50:51] offset:3072 sc1
	global_load_dword v2, v177, s[50:51] offset:3328 sc1
	global_load_dword v1, v177, s[50:51] offset:3584 sc1
	global_load_dword v0, v177, s[50:51] offset:3840 sc1
	v_readlane_b32 s5, v254, 6
	s_waitcnt vmcnt(13)
	v_add_u32_e32 v16, v14, v15
	s_nop 2
	global_load_dword v3, v177, s[4:5] sc1
	s_waitcnt vmcnt(13)
	v_add_u32_e32 v16, v16, v13
	s_waitcnt vmcnt(12)
	v_add_u32_e32 v16, v16, v12
	s_waitcnt vmcnt(11)
	v_add_u32_e32 v16, v16, v11
	s_waitcnt vmcnt(10)
	v_add_u32_e32 v16, v16, v10
	s_waitcnt vmcnt(9)
	v_add_u32_e32 v16, v16, v9
	s_waitcnt vmcnt(8)
	v_add_u32_e32 v16, v16, v8
	s_waitcnt vmcnt(7)
	v_add_u32_e32 v16, v16, v7
	s_waitcnt vmcnt(6)
	v_add_u32_e32 v16, v16, v6
	s_waitcnt vmcnt(5)
	v_add_u32_e32 v16, v16, v5
	s_waitcnt vmcnt(4)
	v_add_u32_e32 v16, v16, v4
	s_waitcnt vmcnt(3)
	v_add_u32_e32 v16, v16, v2
	s_waitcnt vmcnt(2)
	v_add_u32_e32 v16, v16, v1
	s_waitcnt vmcnt(1)
	v_add_u32_e32 v16, v16, v0
	v_readlane_b32 s4, v253, 1
	s_waitcnt vmcnt(0)
	v_add_u32_e32 v16, v16, v3
	v_cmp_ne_u32_e32 vcc, s4, v16
	s_mov_b64 s[4:5], -1
	s_cbranch_vccz .LBB0_165
	s_sleep 4
	s_add_i32 s7, s7, -2
	s_mov_b64 s[4:5], 0
	s_branch .LBB0_165

.LBB0_180:
	global_load_dword v0, v177, s[6:7] sc1
	s_or_b64 s[10:11], s[10:11], exec
	s_waitcnt vmcnt(0)
	v_cmp_eq_u32_e32 vcc, v0, v1
	s_and_saveexec_b64 s[12:13], vcc
	s_cbranch_execz .LBB0_179
	s_sleep 4
	global_load_dword v0, v177, s[6:7] sc1
	s_mov_b64 s[16:17], -1
	s_waitcnt vmcnt(0)
	v_cmp_eq_u32_e32 vcc, v0, v1
	s_and_saveexec_b64 s[14:15], vcc
	s_cbranch_execz .LBB0_178
	s_sleep 4
	global_load_dword v0, v177, s[6:7] sc1
	s_mov_b64 s[18:19], -1
	s_waitcnt vmcnt(0)
	v_cmp_eq_u32_e32 vcc, v0, v1
	s_and_saveexec_b64 s[16:17], vcc
	s_cbranch_execz .LBB0_177
	s_sleep 4
	global_load_dword v0, v177, s[6:7] sc1
	s_mov_b64 s[20:21], -1
	s_waitcnt vmcnt(0)
	v_cmp_eq_u32_e32 vcc, v0, v1
	s_and_saveexec_b64 s[18:19], vcc
	s_cbranch_execz .LBB0_176
	s_sleep 4
	global_load_dword v0, v177, s[6:7] sc1
	s_waitcnt vmcnt(0)
	v_cmp_eq_u32_e32 vcc, v0, v1
	s_and_saveexec_b64 s[22:23], vcc
	s_cbranch_execz .LBB0_175
	s_add_i32 s24, s24, -5
	s_cmp_eq_u32 s24, 0
	s_cselect_b64 s[20:21], -1, 0
	s_orn2_b64 s[20:21], s[20:21], exec
	s_sleep 4
	s_branch .LBB0_175

.LBB0_197:
	v_readlane_b32 s10, v254, 9
	v_readlane_b32 s11, v254, 10
	s_or_b64 s[8:9], s[8:9], exec
	s_nop 3
	global_load_dword v0, v177, s[10:11] sc1
	s_waitcnt vmcnt(0)
	v_cmp_eq_u32_e32 vcc, v0, v1
	s_and_saveexec_b64 s[10:11], vcc
	s_cbranch_execz .LBB0_196
	v_readlane_b32 s12, v254, 9
	v_readlane_b32 s13, v254, 10
	s_sleep 4
	s_mov_b64 s[14:15], -1
	s_nop 2
	global_load_dword v0, v177, s[12:13] sc1
	s_waitcnt vmcnt(0)
	v_cmp_eq_u32_e32 vcc, v0, v1
	s_and_saveexec_b64 s[12:13], vcc
	s_cbranch_execz .LBB0_195
	v_readlane_b32 s14, v254, 9
	v_readlane_b32 s15, v254, 10
	s_sleep 4
	s_mov_b64 s[16:17], -1
	s_nop 2
	global_load_dword v0, v177, s[14:15] sc1
	s_waitcnt vmcnt(0)
	v_cmp_eq_u32_e32 vcc, v0, v1
	s_and_saveexec_b64 s[14:15], vcc
	s_cbranch_execz .LBB0_194
	v_readlane_b32 s16, v254, 9
	v_readlane_b32 s17, v254, 10
	s_sleep 4
	s_mov_b64 s[18:19], -1
	s_nop 2
	global_load_dword v0, v177, s[16:17] sc1
	s_waitcnt vmcnt(0)
	v_cmp_eq_u32_e32 vcc, v0, v1
	s_and_saveexec_b64 s[16:17], vcc
	s_cbranch_execz .LBB0_193
	v_readlane_b32 s18, v254, 9
	v_readlane_b32 s19, v254, 10
	s_sleep 4
	s_nop 3
	global_load_dword v0, v177, s[18:19] sc1
	s_mov_b64 s[18:19], -1
	s_waitcnt vmcnt(0)
	v_cmp_eq_u32_e32 vcc, v0, v1
	s_and_saveexec_b64 s[20:21], vcc
	s_cbranch_execz .LBB0_192
	s_add_i32 s22, s22, -5
	s_cmp_eq_u32 s22, 0
	s_cselect_b64 s[18:19], -1, 0
	s_orn2_b64 s[18:19], s[18:19], exec
	s_sleep 4
	s_branch .LBB0_192

.LBB0_890:
	global_load_dword v0, v177, s[6:7] sc1
	s_or_b64 s[10:11], s[10:11], exec
	s_waitcnt vmcnt(0)
	v_cmp_eq_u32_e32 vcc, v0, v1
	s_and_saveexec_b64 s[12:13], vcc
	s_cbranch_execz .LBB0_889
	s_sleep 4
	global_load_dword v0, v177, s[6:7] sc1
	s_mov_b64 s[16:17], -1
	s_waitcnt vmcnt(0)
	v_cmp_eq_u32_e32 vcc, v0, v1
	s_and_saveexec_b64 s[14:15], vcc
	s_cbranch_execz .LBB0_888
	s_sleep 4
	global_load_dword v0, v177, s[6:7] sc1
	s_mov_b64 s[18:19], -1
	s_waitcnt vmcnt(0)
	v_cmp_eq_u32_e32 vcc, v0, v1
	s_and_saveexec_b64 s[16:17], vcc
	s_cbranch_execz .LBB0_887
	s_sleep 4
	global_load_dword v0, v177, s[6:7] sc1
	s_mov_b64 s[20:21], -1
	s_waitcnt vmcnt(0)
	v_cmp_eq_u32_e32 vcc, v0, v1
	s_and_saveexec_b64 s[18:19], vcc
	s_cbranch_execz .LBB0_886
	s_sleep 4
	global_load_dword v0, v177, s[6:7] sc1
	s_waitcnt vmcnt(0)
	v_cmp_eq_u32_e32 vcc, v0, v1
	s_and_saveexec_b64 s[22:23], vcc
	s_cbranch_execz .LBB0_885
	s_add_i32 s25, s25, -5
	s_cmp_eq_u32 s25, 0
	s_cselect_b64 s[20:21], -1, 0
	s_orn2_b64 s[20:21], s[20:21], exec
	s_sleep 4
	s_branch .LBB0_885

.LBB0_945:
	global_load_dword v0, v177, s[6:7] sc1
	s_or_b64 s[10:11], s[10:11], exec
	s_waitcnt vmcnt(0)
	v_cmp_eq_u32_e32 vcc, v0, v1
	s_and_saveexec_b64 s[12:13], vcc
	s_cbranch_execz .LBB0_944
	s_sleep 4
	global_load_dword v0, v177, s[6:7] sc1
	s_mov_b64 s[16:17], -1
	s_waitcnt vmcnt(0)
	v_cmp_eq_u32_e32 vcc, v0, v1
	s_and_saveexec_b64 s[14:15], vcc
	s_cbranch_execz .LBB0_943
	s_sleep 4
	global_load_dword v0, v177, s[6:7] sc1
	s_mov_b64 s[18:19], -1
	s_waitcnt vmcnt(0)
	v_cmp_eq_u32_e32 vcc, v0, v1
	s_and_saveexec_b64 s[16:17], vcc
	s_cbranch_execz .LBB0_942
	s_sleep 4
	global_load_dword v0, v177, s[6:7] sc1
	s_mov_b64 s[20:21], -1
	s_waitcnt vmcnt(0)
	v_cmp_eq_u32_e32 vcc, v0, v1
	s_and_saveexec_b64 s[18:19], vcc
	s_cbranch_execz .LBB0_941
	s_sleep 4
	global_load_dword v0, v177, s[6:7] sc1
	s_waitcnt vmcnt(0)
	v_cmp_eq_u32_e32 vcc, v0, v1
	s_and_saveexec_b64 s[22:23], vcc
	s_cbranch_execz .LBB0_940
	s_add_i32 s27, s27, -5
	s_cmp_eq_u32 s27, 0
	s_cselect_b64 s[20:21], -1, 0
	s_orn2_b64 s[20:21], s[20:21], exec
	s_sleep 4
	s_branch .LBB0_940
